# conv2d: hoist the 4 per-row UV loads of each column step above the first store (1 wait per step instead of 4); conv1d: 8-row fast path with one load batch per block
# speedup vs baseline: 1.0287x; 1.0128x over previous
.Lc1_top:
	v_readfirstlane_b32 s84, v43
	v_readfirstlane_b32 s85, v104
	s_nop 1
	s_add_u32 s88, s84, 8
	s_cmp_gt_u32 s88, s85
	s_cbranch_scc1 .LBB0_360
	s_cmp_gt_u32 s88, 0x10000
	s_cbranch_scc1 .LBB0_360
	s_and_b32 s88, s84, 0x1fff
	s_cmp_lt_u32 s88, 2
	s_cbranch_scc1 .LBB0_360
	s_cmp_gt_u32 s88, 0x1ff7
	s_cbranch_scc1 .LBB0_360
	v_readfirstlane_b32 s86, v54
	v_readfirstlane_b32 s87, v55
	v_readfirstlane_b32 s88, v36
	v_readfirstlane_b32 s94, v56
	v_readfirstlane_b32 s95, v57
	v_lshlrev_b32_e32 v252, 1, v36
	s_nop 1
	s_lshl_b32 s88, s88, 1
	v_subrev_u32_e32 v252, s88, v252
	s_add_u32 s86, s86, s88
	s_addc_u32 s87, s87, 0
	s_sub_u32 s92, s86, 0x6800
	s_subb_u32 s93, s87, 0
	global_load_dwordx2 v[208:209], v252, s[92:93]
	s_add_u32 s92, s92, 0x3400
	s_addc_u32 s93, s93, 0
	global_load_dwordx2 v[212:213], v252, s[92:93]
	s_add_u32 s92, s92, 0x3400
	s_addc_u32 s93, s93, 0
	global_load_dwordx2 v[216:217], v252, s[92:93]
	s_add_u32 s92, s92, 0x3400
	s_addc_u32 s93, s93, 0
	global_load_dwordx2 v[220:221], v252, s[92:93]
	s_add_u32 s92, s92, 0x3400
	s_addc_u32 s93, s93, 0
	global_load_dwordx2 v[224:225], v252, s[92:93]
	s_add_u32 s92, s92, 0x3400
	s_addc_u32 s93, s93, 0
	global_load_dwordx2 v[228:229], v252, s[92:93]
	s_add_u32 s92, s92, 0x3400
	s_addc_u32 s93, s93, 0
	global_load_dwordx2 v[232:233], v252, s[92:93]
	s_add_u32 s92, s92, 0x3400
	s_addc_u32 s93, s93, 0
	global_load_dwordx2 v[236:237], v252, s[92:93]
	s_add_u32 s92, s92, 0x3400
	s_addc_u32 s93, s93, 0
	global_load_dwordx2 v[240:241], v252, s[92:93]
	s_add_u32 s92, s92, 0x3400
	s_addc_u32 s93, s93, 0
	global_load_dwordx2 v[244:245], v252, s[92:93]
	s_add_u32 s92, s92, 0x3400
	s_addc_u32 s93, s93, 0
	global_load_dwordx2 v[248:249], v252, s[92:93]
	s_waitcnt vmcnt(0)
	v_lshlrev_b32_e32 v210, 16, v209
	v_and_b32_e32 v211, 0xffff0000, v209
	v_and_b32_e32 v209, 0xffff0000, v208
	v_lshlrev_b32_e32 v208, 16, v208
	v_lshlrev_b32_e32 v214, 16, v213
	v_and_b32_e32 v215, 0xffff0000, v213
	v_and_b32_e32 v213, 0xffff0000, v212
	v_lshlrev_b32_e32 v212, 16, v212
	v_lshlrev_b32_e32 v218, 16, v217
	v_and_b32_e32 v219, 0xffff0000, v217
	v_and_b32_e32 v217, 0xffff0000, v216
	v_lshlrev_b32_e32 v216, 16, v216
	v_lshlrev_b32_e32 v222, 16, v221
	v_and_b32_e32 v223, 0xffff0000, v221
	v_and_b32_e32 v221, 0xffff0000, v220
	v_lshlrev_b32_e32 v220, 16, v220
	v_lshlrev_b32_e32 v226, 16, v225
	v_and_b32_e32 v227, 0xffff0000, v225
	v_and_b32_e32 v225, 0xffff0000, v224
	v_lshlrev_b32_e32 v224, 16, v224
	v_lshlrev_b32_e32 v230, 16, v229
	v_and_b32_e32 v231, 0xffff0000, v229
	v_and_b32_e32 v229, 0xffff0000, v228
	v_lshlrev_b32_e32 v228, 16, v228
	v_lshlrev_b32_e32 v234, 16, v233
	v_and_b32_e32 v235, 0xffff0000, v233
	v_and_b32_e32 v233, 0xffff0000, v232
	v_lshlrev_b32_e32 v232, 16, v232
	v_lshlrev_b32_e32 v238, 16, v237
	v_and_b32_e32 v239, 0xffff0000, v237
	v_and_b32_e32 v237, 0xffff0000, v236
	v_lshlrev_b32_e32 v236, 16, v236
	v_lshlrev_b32_e32 v242, 16, v241
	v_and_b32_e32 v243, 0xffff0000, v241
	v_and_b32_e32 v241, 0xffff0000, v240
	v_lshlrev_b32_e32 v240, 16, v240
	v_lshlrev_b32_e32 v246, 16, v245
	v_and_b32_e32 v247, 0xffff0000, v245
	v_and_b32_e32 v245, 0xffff0000, v244
	v_lshlrev_b32_e32 v244, 16, v244
	v_lshlrev_b32_e32 v250, 16, v249
	v_and_b32_e32 v251, 0xffff0000, v249
	v_and_b32_e32 v249, 0xffff0000, v248
	v_lshlrev_b32_e32 v248, 16, v248
	v_pk_fma_f32 v[208:209], v[0:1], v[208:209], v[16:17]
	v_pk_fma_f32 v[210:211], v[2:3], v[210:211], v[18:19]
	v_pk_fma_f32 v[208:209], v[4:5], v[212:213], v[208:209]
	v_pk_fma_f32 v[210:211], v[6:7], v[214:215], v[210:211]
	v_pk_fma_f32 v[208:209], v[8:9], v[216:217], v[208:209]
	v_pk_fma_f32 v[210:211], v[10:11], v[218:219], v[210:211]
	v_pk_fma_f32 v[208:209], v[12:13], v[220:221], v[208:209]
	v_pk_fma_f32 v[210:211], v[14:15], v[222:223], v[210:211]
	v_cvt_pk_bf16_f32 v208, v208, v209
	v_cvt_pk_bf16_f32 v209, v210, v211
	global_store_dwordx2 v252, v[208:209], s[94:95]
	s_add_u32 s94, s94, 0xa00
	s_addc_u32 s95, s95, 0
	v_pk_fma_f32 v[212:213], v[0:1], v[212:213], v[16:17]
	v_pk_fma_f32 v[214:215], v[2:3], v[214:215], v[18:19]
	v_pk_fma_f32 v[212:213], v[4:5], v[216:217], v[212:213]
	v_pk_fma_f32 v[214:215], v[6:7], v[218:219], v[214:215]
	v_pk_fma_f32 v[212:213], v[8:9], v[220:221], v[212:213]
	v_pk_fma_f32 v[214:215], v[10:11], v[222:223], v[214:215]
	v_pk_fma_f32 v[212:213], v[12:13], v[224:225], v[212:213]
	v_pk_fma_f32 v[214:215], v[14:15], v[226:227], v[214:215]
	v_cvt_pk_bf16_f32 v212, v212, v213
	v_cvt_pk_bf16_f32 v213, v214, v215
	global_store_dwordx2 v252, v[212:213], s[94:95]
	s_add_u32 s94, s94, 0xa00
	s_addc_u32 s95, s95, 0
	v_pk_fma_f32 v[216:217], v[0:1], v[216:217], v[16:17]
	v_pk_fma_f32 v[218:219], v[2:3], v[218:219], v[18:19]
	v_pk_fma_f32 v[216:217], v[4:5], v[220:221], v[216:217]
	v_pk_fma_f32 v[218:219], v[6:7], v[222:223], v[218:219]
	v_pk_fma_f32 v[216:217], v[8:9], v[224:225], v[216:217]
	v_pk_fma_f32 v[218:219], v[10:11], v[226:227], v[218:219]
	v_pk_fma_f32 v[216:217], v[12:13], v[228:229], v[216:217]
	v_pk_fma_f32 v[218:219], v[14:15], v[230:231], v[218:219]
	v_cvt_pk_bf16_f32 v216, v216, v217
	v_cvt_pk_bf16_f32 v217, v218, v219
	global_store_dwordx2 v252, v[216:217], s[94:95]
	s_add_u32 s94, s94, 0xa00
	s_addc_u32 s95, s95, 0
	v_pk_fma_f32 v[220:221], v[0:1], v[220:221], v[16:17]
	v_pk_fma_f32 v[222:223], v[2:3], v[222:223], v[18:19]
	v_pk_fma_f32 v[220:221], v[4:5], v[224:225], v[220:221]
	v_pk_fma_f32 v[222:223], v[6:7], v[226:227], v[222:223]
	v_pk_fma_f32 v[220:221], v[8:9], v[228:229], v[220:221]
	v_pk_fma_f32 v[222:223], v[10:11], v[230:231], v[222:223]
	v_pk_fma_f32 v[220:221], v[12:13], v[232:233], v[220:221]
	v_pk_fma_f32 v[222:223], v[14:15], v[234:235], v[222:223]
	v_cvt_pk_bf16_f32 v220, v220, v221
	v_cvt_pk_bf16_f32 v221, v222, v223
	global_store_dwordx2 v252, v[220:221], s[94:95]
	s_add_u32 s94, s94, 0xa00
	s_addc_u32 s95, s95, 0
	v_pk_fma_f32 v[224:225], v[0:1], v[224:225], v[16:17]
	v_pk_fma_f32 v[226:227], v[2:3], v[226:227], v[18:19]
	v_pk_fma_f32 v[224:225], v[4:5], v[228:229], v[224:225]
	v_pk_fma_f32 v[226:227], v[6:7], v[230:231], v[226:227]
	v_pk_fma_f32 v[224:225], v[8:9], v[232:233], v[224:225]
	v_pk_fma_f32 v[226:227], v[10:11], v[234:235], v[226:227]
	v_pk_fma_f32 v[224:225], v[12:13], v[236:237], v[224:225]
	v_pk_fma_f32 v[226:227], v[14:15], v[238:239], v[226:227]
	v_cvt_pk_bf16_f32 v224, v224, v225
	v_cvt_pk_bf16_f32 v225, v226, v227
	global_store_dwordx2 v252, v[224:225], s[94:95]
	s_add_u32 s94, s94, 0xa00
	s_addc_u32 s95, s95, 0
	v_pk_fma_f32 v[228:229], v[0:1], v[228:229], v[16:17]
	v_pk_fma_f32 v[230:231], v[2:3], v[230:231], v[18:19]
	v_pk_fma_f32 v[228:229], v[4:5], v[232:233], v[228:229]
	v_pk_fma_f32 v[230:231], v[6:7], v[234:235], v[230:231]
	v_pk_fma_f32 v[228:229], v[8:9], v[236:237], v[228:229]
	v_pk_fma_f32 v[230:231], v[10:11], v[238:239], v[230:231]
	v_pk_fma_f32 v[228:229], v[12:13], v[240:241], v[228:229]
	v_pk_fma_f32 v[230:231], v[14:15], v[242:243], v[230:231]
	v_cvt_pk_bf16_f32 v228, v228, v229
	v_cvt_pk_bf16_f32 v229, v230, v231
	global_store_dwordx2 v252, v[228:229], s[94:95]
	s_add_u32 s94, s94, 0xa00
	s_addc_u32 s95, s95, 0
	v_pk_fma_f32 v[232:233], v[0:1], v[232:233], v[16:17]
	v_pk_fma_f32 v[234:235], v[2:3], v[234:235], v[18:19]
	v_pk_fma_f32 v[232:233], v[4:5], v[236:237], v[232:233]
	v_pk_fma_f32 v[234:235], v[6:7], v[238:239], v[234:235]
	v_pk_fma_f32 v[232:233], v[8:9], v[240:241], v[232:233]
	v_pk_fma_f32 v[234:235], v[10:11], v[242:243], v[234:235]
	v_pk_fma_f32 v[232:233], v[12:13], v[244:245], v[232:233]
	v_pk_fma_f32 v[234:235], v[14:15], v[246:247], v[234:235]
	v_cvt_pk_bf16_f32 v232, v232, v233
	v_cvt_pk_bf16_f32 v233, v234, v235
	global_store_dwordx2 v252, v[232:233], s[94:95]
	s_add_u32 s94, s94, 0xa00
	s_addc_u32 s95, s95, 0
	v_pk_fma_f32 v[236:237], v[0:1], v[236:237], v[16:17]
	v_pk_fma_f32 v[238:239], v[2:3], v[238:239], v[18:19]
	v_pk_fma_f32 v[236:237], v[4:5], v[240:241], v[236:237]
	v_pk_fma_f32 v[238:239], v[6:7], v[242:243], v[238:239]
	v_pk_fma_f32 v[236:237], v[8:9], v[244:245], v[236:237]
	v_pk_fma_f32 v[238:239], v[10:11], v[246:247], v[238:239]
	v_pk_fma_f32 v[236:237], v[12:13], v[248:249], v[236:237]
	v_pk_fma_f32 v[238:239], v[14:15], v[250:251], v[238:239]
	v_cvt_pk_bf16_f32 v236, v236, v237
	v_cvt_pk_bf16_f32 v237, v238, v239
	global_store_dwordx2 v252, v[236:237], s[94:95]
	s_mov_b32 s66, 0x1a000
	s_mov_b32 s67, 0
	s_mov_b32 s68, 0x5000
	s_mov_b32 s69, 0
	v_add_u32_e32 v43, 8, v43
	v_lshl_add_u64 v[54:55], v[54:55], 0, s[66:67]
	v_lshl_add_u64 v[56:57], v[56:57], 0, s[68:69]
	s_add_u32 s84, s84, 8
	s_cmp_lt_u32 s84, s85
	s_cbranch_scc1 .Lc1_top
	s_branch .LBB0_344
